# more LDS lane shuffles replaced: norm-phase 16-lane reduction (DPP), indexer histogram / radix-select wave prefix scans (DPP row_shr + row_bcast instead of six ds_bpermute round trips each)
# speedup vs baseline: 1.0023x; 1.0023x over previous
; #define LAS __attribute__((address_space(3)))
; __device__ __forceinline__ void wave_find(unsigned c, unsigned need, int lane, int& sl, unsigned& excl_at) {
;     unsigned incl = c;
; #pragma unroll
;     for (int o = 1; o < 64; o <<= 1) { const unsigned t = __shfl_up(incl, o); if (lane >= o) incl += t; }
;     const unsigned excl = incl - c;
;     const unsigned long long b = __builtin_amdgcn_ballot_w64(excl < need && need <= incl);
;     sl = b ? (int)__builtin_ctzll(b) : 63;
;     excl_at = __shfl(excl, sl);
; }
; __device__ __forceinline__ bool indexer_fast(LAS unsigned char* lds, const bf16_t* H, unsigned char* MASKB, int bl, int qb) {
;     ...
;     for (int r = 0; r < 4; ++r) {
;         const int row = wid * 4 + r;
;         if (q0 + row < 256) { if (lane == 0) { tbin[row] = -1; need1[row] = 0u; } continue; }
;         const LAS unsigned* hp = H11 + row * 1025 + 1008 - 16 * lane;
;         unsigned c = 0u;
; #pragma unroll
;         for (int i = 0; i < 16; ++i) { const unsigned w = hp[i]; c += (w & 0xffffu) + (w >> 16); }
;         int L1; unsigned ex1; wave_find(c, 256u, lane, L1, ex1);
;         const int top = 2047 - 32 * L1; const unsigned need2 = 256u - ex1;
;         unsigned c2 = 0u;
;         if (lane < 32) { const int bin = top - lane; const unsigned w = H11[row * 1025 + (bin >> 1)]; c2 = (bin & 1) ? (w >> 16) : (w & 0xffffu); }
;         int L2; unsigned ex2; wave_find(c2, need2, lane, L2, ex2);
;         if (lane == 0) { tbin[row] = top - L2; need1[row] = need2 - ex2; }
;     }
.LBB0_448:
	s_lshl_b32 s16, s12, 2
	v_and_b32_e32 v180, 63, v217
	s_add_i32 s0, s16, s17
	v_mul_i32_i24_e32 v0, 0xffffffc0, v180
	v_cmp_eq_u32_e64 s[36:37], 0, v180
	v_cmp_gt_u32_e64 s[38:39], 2, v180
	v_cmp_gt_u32_e64 s[40:41], 4, v180
	v_cmp_gt_u32_e64 s[42:43], 8, v180
	v_cmp_gt_u32_e64 s[44:45], 16, v180
	v_cmp_gt_u32_e64 s[46:47], 32, v180
	s_cmpk_gt_i32 s0, 0xff
	s_mov_b64 s[0:1], -1
	s_waitcnt lgkmcnt(0)
	s_barrier
	s_cbranch_scc0 .LBB0_454
	s_mul_i32 s0, s12, 0x4010
	s_add_i32 s13, s0, 0
	v_add_u32_e32 v94, s13, v0
	ds_read_b128 v[82:85], v94 offset:4032
	ds_read_b128 v[86:89], v94 offset:4048
	ds_read_b128 v[90:93], v94 offset:4064
	ds_read_b128 v[94:97], v94 offset:4080
	s_movk_i32 s0, 0xff
	s_waitcnt lgkmcnt(3)
	v_add_u32_sdwa v82, v82, v82 dst_sel:DWORD dst_unused:UNUSED_PAD src0_sel:WORD_1 src1_sel:WORD_0
	v_and_b32_e32 v98, 0xffff, v83
	v_lshrrev_b32_e32 v83, 16, v83
	v_add3_u32 v82, v82, v83, v98
	v_and_b32_e32 v83, 0xffff, v84
	v_lshrrev_b32_e32 v84, 16, v84
	v_add3_u32 v82, v82, v84, v83
	v_and_b32_e32 v83, 0xffff, v85
	v_lshrrev_b32_e32 v84, 16, v85
	v_add3_u32 v82, v82, v84, v83
	s_waitcnt lgkmcnt(2)
	v_and_b32_e32 v83, 0xffff, v86
	v_lshrrev_b32_e32 v84, 16, v86
	v_add3_u32 v82, v82, v84, v83
	v_and_b32_e32 v83, 0xffff, v87
	v_lshrrev_b32_e32 v84, 16, v87
	v_add3_u32 v82, v82, v84, v83
	v_and_b32_e32 v83, 0xffff, v88
	v_lshrrev_b32_e32 v84, 16, v88
	v_add3_u32 v82, v82, v84, v83
	v_and_b32_e32 v83, 0xffff, v89
	v_lshrrev_b32_e32 v84, 16, v89
	v_add3_u32 v82, v82, v84, v83
	s_waitcnt lgkmcnt(1)
	v_and_b32_e32 v83, 0xffff, v90
	v_lshrrev_b32_e32 v84, 16, v90
	v_add3_u32 v82, v82, v84, v83
	v_and_b32_e32 v83, 0xffff, v91
	v_lshrrev_b32_e32 v84, 16, v91
	v_add3_u32 v82, v82, v84, v83
	v_and_b32_e32 v83, 0xffff, v92
	v_lshrrev_b32_e32 v84, 16, v92
	v_add3_u32 v82, v82, v84, v83
	v_and_b32_e32 v83, 0xffff, v93
	v_lshrrev_b32_e32 v84, 16, v93
	v_add3_u32 v82, v82, v84, v83
	s_waitcnt lgkmcnt(0)
	v_and_b32_e32 v83, 0xffff, v94
	v_lshrrev_b32_e32 v84, 16, v94
	v_add3_u32 v82, v82, v84, v83
	v_and_b32_e32 v83, 0xffff, v95
	v_lshrrev_b32_e32 v84, 16, v95
	v_add3_u32 v82, v82, v84, v83
	v_and_b32_e32 v83, 0xffff, v96
	v_lshrrev_b32_e32 v84, 16, v96
	v_add3_u32 v82, v82, v84, v83
	v_and_b32_e32 v83, 0xffff, v97
	v_lshrrev_b32_e32 v84, 16, v97
	v_add3_u32 v88, v82, v84, v83
	v_add_u32_e32 v82, -1, v197
	v_cmp_lt_i32_e32 vcc, v82, v198
	s_nop 1
	v_cndmask_b32_e32 v82, v82, v197, vcc
	v_lshlrev_b32_e32 v82, 2, v82
	v_mov_b32_e32 v84, v88
	s_waitcnt lgkmcnt(0)
	s_nop 1
	v_add_u32_dpp v84, v84, v84 row_shr:1 row_mask:0xf bank_mask:0xf
	v_add_u32_e32 v83, -2, v197
	v_cmp_lt_i32_e32 vcc, v83, v198
	s_nop 1
	v_cndmask_b32_e32 v83, v83, v197, vcc
	v_lshlrev_b32_e32 v83, 2, v83
	v_mov_b32_e32 v85, v84
	s_waitcnt lgkmcnt(0)
	s_nop 1
	v_add_u32_dpp v85, v85, v85 row_shr:2 row_mask:0xf bank_mask:0xf
	v_add_u32_e32 v84, -4, v197
	v_cmp_lt_i32_e32 vcc, v84, v198
	s_nop 1
	v_cndmask_b32_e32 v84, v84, v197, vcc
	v_lshlrev_b32_e32 v84, 2, v84
	v_mov_b32_e32 v86, v85
	s_waitcnt lgkmcnt(0)
	s_nop 1
	v_add_u32_dpp v86, v86, v86 row_shr:4 row_mask:0xf bank_mask:0xf
	v_add_u32_e32 v85, -8, v197
	v_cmp_lt_i32_e32 vcc, v85, v198
	s_nop 1
	v_cndmask_b32_e32 v85, v85, v197, vcc
	v_lshlrev_b32_e32 v85, 2, v85
	v_mov_b32_e32 v87, v86
	s_waitcnt lgkmcnt(0)
	s_nop 1
	v_add_u32_dpp v87, v87, v87 row_shr:8 row_mask:0xf bank_mask:0xf
	v_add_u32_e32 v86, -16, v197
	v_cmp_lt_i32_e32 vcc, v86, v198
	s_nop 1
	v_cndmask_b32_e32 v86, v86, v197, vcc
	v_lshlrev_b32_e32 v86, 2, v86
	v_mov_b32_e32 v89, v87
	s_waitcnt lgkmcnt(0)
	s_nop 1
	v_add_u32_dpp v89, v89, v89 row_bcast:15 row_mask:0xa bank_mask:0xf
	v_subrev_u32_e32 v87, 32, v197
	v_cmp_lt_i32_e32 vcc, v87, v198
	s_nop 1
	v_cndmask_b32_e32 v87, v87, v197, vcc
	v_lshlrev_b32_e32 v87, 2, v87
	s_nop 0
	s_waitcnt lgkmcnt(0)
	s_nop 1
	v_add_u32_dpp v89, v89, v89 row_bcast:31 row_mask:0xc bank_mask:0xf
	v_sub_u32_e32 v88, v89, v88
	v_cmp_gt_u32_e32 vcc, s79, v88
	v_cmp_lt_u32_e64 s[0:1], s0, v89
	s_and_b64 s[0:1], s[0:1], vcc
	s_nop 0
	v_cndmask_b32_e64 v89, 0, 1, s[0:1]
	v_cmp_ne_u32_e32 vcc, 0, v89
	s_ff1_i32_b64 s0, vcc
	s_cmp_lg_u64 vcc, 0
	s_cselect_b32 s0, s0, 63
	v_or_b32_e32 v89, s0, v198
	v_lshlrev_b32_e32 v89, 2, v89
	ds_bpermute_b32 v88, v89, v88
	s_lshl_b32 s0, s0, 5
	v_mov_b32_e32 v89, 0
	s_xor_b32 s14, s0, 0x7ff
	s_and_saveexec_b64 s[0:1], s[46:47]
	s_cbranch_execz .LBB0_451
	v_sub_u32_e32 v89, s14, v180
	v_lshlrev_b32_e32 v90, 1, v89
	v_and_b32_e32 v90, -4, v90
	v_add_u32_e32 v90, s13, v90
	ds_read_b32 v90, v90
	v_and_b32_e32 v89, 1, v89
	v_cmp_eq_u32_e32 vcc, 0, v89
	s_waitcnt lgkmcnt(0)
	s_nop 0
	v_cndmask_b32_sdwa v89, v90, v90, vcc dst_sel:DWORD dst_unused:UNUSED_PAD src0_sel:WORD_1 src1_sel:WORD_0
.LBB0_451:
	s_or_b64 exec, exec, s[0:1]
	v_mov_b32_e32 v82, v89
	s_waitcnt lgkmcnt(0)
	s_nop 1
	v_add_u32_dpp v82, v82, v82 row_shr:1 row_mask:0xf bank_mask:0xf
	s_nop 0
	s_waitcnt lgkmcnt(0)
	s_nop 1
	v_add_u32_dpp v82, v82, v82 row_shr:2 row_mask:0xf bank_mask:0xf
	s_nop 0
	s_waitcnt lgkmcnt(0)
	s_nop 1
	v_add_u32_dpp v82, v82, v82 row_shr:4 row_mask:0xf bank_mask:0xf
	s_nop 0
	s_waitcnt lgkmcnt(0)
	s_nop 1
	v_add_u32_dpp v82, v82, v82 row_shr:8 row_mask:0xf bank_mask:0xf
	v_mov_b32_e32 v83, v82
	s_waitcnt lgkmcnt(0)
	s_nop 1
	v_add_u32_dpp v83, v83, v83 row_bcast:15 row_mask:0xa bank_mask:0xf
	s_nop 0
	v_sub_u32_e32 v82, 0x100, v88
	s_waitcnt lgkmcnt(0)
	s_nop 1
	v_add_u32_dpp v83, v83, v83 row_bcast:31 row_mask:0xc bank_mask:0xf
	v_sub_u32_e32 v84, v83, v89
	v_cmp_le_u32_e32 vcc, v82, v83
	v_cmp_lt_u32_e64 s[0:1], v84, v82
	s_and_b64 s[0:1], vcc, s[0:1]
	s_nop 0
	v_cndmask_b32_e64 v83, 0, 1, s[0:1]
	v_cmp_ne_u32_e32 vcc, 0, v83
	s_ff1_i32_b64 s0, vcc
	s_cmp_lg_u64 vcc, 0
	s_cselect_b32 s13, s0, 63
	v_or_b32_e32 v83, s13, v198
	v_lshlrev_b32_e32 v83, 2, v83
	ds_bpermute_b32 v83, v83, v84
	s_and_saveexec_b64 s[0:1], s[36:37]
	s_cbranch_execz .LBB0_453
	s_sub_i32 s13, s14, s13
	s_lshl_b32 s14, s16, 2
	s_add_i32 s14, s14, 0
	s_add_i32 s15, s14, 0x20180
	s_waitcnt lgkmcnt(0)
	v_sub_u32_e32 v82, v82, v83
	s_add_i32 s14, s14, 0x20200
	v_mov_b32_e32 v83, s15
	v_mov_b32_e32 v84, s13
	ds_write_b32 v83, v84
	v_mov_b32_e32 v83, s14
	ds_write_b32 v83, v82

; #define LAS __attribute__((address_space(3)))
; __device__ __forceinline__ void wave_find(unsigned c, unsigned need, int lane, int& sl, unsigned& excl_at) {
;     unsigned incl = c;
; #pragma unroll
;     for (int o = 1; o < 64; o <<= 1) { const unsigned t = __shfl_up(incl, o); if (lane >= o) incl += t; }
;     const unsigned excl = incl - c;
;     const unsigned long long b = __builtin_amdgcn_ballot_w64(excl < need && need <= incl);
;     sl = b ? (int)__builtin_ctzll(b) : 63;
;     excl_at = __shfl(excl, sl);
; }
; __device__ __forceinline__ bool indexer_fast(LAS unsigned char* lds, const bf16_t* H, unsigned char* MASKB, int bl, int qb) {
;     ...
;     for (int r = 0; r < 4; ++r) {
;         const int row = wid * 4 + r;
;         if (q0 + row < 256) { if (lane == 0) { tbin[row] = -1; need1[row] = 0u; } continue; }
;         const LAS unsigned* hp = H11 + row * 1025 + 1008 - 16 * lane;
;         unsigned c = 0u;
; #pragma unroll
;         for (int i = 0; i < 16; ++i) { const unsigned w = hp[i]; c += (w & 0xffffu) + (w >> 16); }
;         int L1; unsigned ex1; wave_find(c, 256u, lane, L1, ex1);
;         const int top = 2047 - 32 * L1; const unsigned need2 = 256u - ex1;
;         unsigned c2 = 0u;
;         if (lane < 32) { const int bin = top - lane; const unsigned w = H11[row * 1025 + (bin >> 1)]; c2 = (bin & 1) ? (w >> 16) : (w & 0xffffu); }
;         int L2; unsigned ex2; wave_find(c2, need2, lane, L2, ex2);
;         if (lane == 0) { tbin[row] = top - L2; need1[row] = need2 - ex2; }
;     }
.LBB0_458:
	s_or_b32 s14, s16, 1
	s_add_i32 s0, s14, s17
	s_cmpk_lt_i32 s0, 0x100
	s_mov_b64 s[0:1], -1
	s_cbranch_scc1 .LBB0_464
	s_mul_i32 s0, s14, 0x1004
	s_add_i32 s13, s0, 0
	v_add_u32_e32 v84, s13, v0
	v_add_u32_e32 v82, 0xfc0, v84
	s_waitcnt lgkmcnt(0)
	ds_read2_b32 v[82:83], v82 offset1:1
	s_movk_i32 s0, 0xff
	s_waitcnt lgkmcnt(0)
	v_add_u32_sdwa v82, v82, v82 dst_sel:DWORD dst_unused:UNUSED_PAD src0_sel:WORD_1 src1_sel:WORD_0
	v_and_b32_e32 v85, 0xffff, v83
	v_lshrrev_b32_e32 v83, 16, v83
	v_add3_u32 v85, v82, v83, v85
	v_add_u32_e32 v82, 0xfc8, v84
	ds_read2_b32 v[82:83], v82 offset1:1
	s_waitcnt lgkmcnt(0)
	v_and_b32_e32 v86, 0xffff, v82
	v_lshrrev_b32_e32 v82, 16, v82
	v_add3_u32 v82, v85, v82, v86
	v_and_b32_e32 v85, 0xffff, v83
	v_lshrrev_b32_e32 v83, 16, v83
	v_add3_u32 v85, v82, v83, v85
	v_add_u32_e32 v82, 0xfd0, v84
	ds_read2_b32 v[82:83], v82 offset1:1
	s_waitcnt lgkmcnt(0)
	v_and_b32_e32 v86, 0xffff, v82
	v_lshrrev_b32_e32 v82, 16, v82
	v_add3_u32 v82, v85, v82, v86
	v_and_b32_e32 v85, 0xffff, v83
	v_lshrrev_b32_e32 v83, 16, v83
	v_add3_u32 v85, v82, v83, v85
	v_add_u32_e32 v82, 0xfd8, v84
	ds_read2_b32 v[82:83], v82 offset1:1
	s_waitcnt lgkmcnt(0)
	v_and_b32_e32 v86, 0xffff, v82
	v_lshrrev_b32_e32 v82, 16, v82
	v_add3_u32 v82, v85, v82, v86
	v_and_b32_e32 v85, 0xffff, v83
	v_lshrrev_b32_e32 v83, 16, v83
	v_add3_u32 v85, v82, v83, v85
	v_add_u32_e32 v82, 0xfe0, v84
	ds_read2_b32 v[82:83], v82 offset1:1
	s_waitcnt lgkmcnt(0)
	v_and_b32_e32 v86, 0xffff, v82
	v_lshrrev_b32_e32 v82, 16, v82
	v_add3_u32 v82, v85, v82, v86
	v_and_b32_e32 v85, 0xffff, v83
	v_lshrrev_b32_e32 v83, 16, v83
	v_add3_u32 v85, v82, v83, v85
	v_add_u32_e32 v82, 0xfe8, v84
	ds_read2_b32 v[82:83], v82 offset1:1
	s_waitcnt lgkmcnt(0)
	v_and_b32_e32 v86, 0xffff, v82
	v_lshrrev_b32_e32 v82, 16, v82
	v_add3_u32 v82, v85, v82, v86
	v_and_b32_e32 v85, 0xffff, v83
	v_lshrrev_b32_e32 v83, 16, v83
	v_add3_u32 v85, v82, v83, v85
	v_add_u32_e32 v82, 0xff0, v84
	ds_read2_b32 v[82:83], v82 offset1:1
	s_waitcnt lgkmcnt(0)
	v_and_b32_e32 v86, 0xffff, v82
	v_lshrrev_b32_e32 v82, 16, v82
	v_add3_u32 v82, v85, v82, v86
	v_and_b32_e32 v85, 0xffff, v83
	v_lshrrev_b32_e32 v83, 16, v83
	v_add3_u32 v85, v82, v83, v85
	v_add_u32_e32 v82, 0xff8, v84
	ds_read2_b32 v[82:83], v82 offset1:1
	s_waitcnt lgkmcnt(0)
	v_and_b32_e32 v84, 0xffff, v82
	v_lshrrev_b32_e32 v82, 16, v82
	v_add3_u32 v82, v85, v82, v84
	v_and_b32_e32 v84, 0xffff, v83
	v_lshrrev_b32_e32 v83, 16, v83
	v_add3_u32 v89, v82, v83, v84
	v_add_u32_e32 v83, -1, v197
	v_cmp_lt_i32_e32 vcc, v83, v198
	v_mov_b32_e32 v82, 0
	s_nop 0
	v_cndmask_b32_e32 v83, v83, v197, vcc
	v_lshlrev_b32_e32 v83, 2, v83
	v_mov_b32_e32 v85, v89
	s_waitcnt lgkmcnt(0)
	s_nop 1
	v_add_u32_dpp v85, v85, v85 row_shr:1 row_mask:0xf bank_mask:0xf
	v_add_u32_e32 v84, -2, v197
	v_cmp_lt_i32_e32 vcc, v84, v198
	s_nop 1
	v_cndmask_b32_e32 v84, v84, v197, vcc
	v_lshlrev_b32_e32 v84, 2, v84
	v_mov_b32_e32 v86, v85
	s_waitcnt lgkmcnt(0)
	s_nop 1
	v_add_u32_dpp v86, v86, v86 row_shr:2 row_mask:0xf bank_mask:0xf
	v_add_u32_e32 v85, -4, v197
	v_cmp_lt_i32_e32 vcc, v85, v198
	s_nop 1
	v_cndmask_b32_e32 v85, v85, v197, vcc
	v_lshlrev_b32_e32 v85, 2, v85
	v_mov_b32_e32 v87, v86
	s_waitcnt lgkmcnt(0)
	s_nop 1
	v_add_u32_dpp v87, v87, v87 row_shr:4 row_mask:0xf bank_mask:0xf
	v_add_u32_e32 v86, -8, v197
	v_cmp_lt_i32_e32 vcc, v86, v198
	s_nop 1
	v_cndmask_b32_e32 v86, v86, v197, vcc
	v_lshlrev_b32_e32 v86, 2, v86
	v_mov_b32_e32 v88, v87
	s_waitcnt lgkmcnt(0)
	s_nop 1
	v_add_u32_dpp v88, v88, v88 row_shr:8 row_mask:0xf bank_mask:0xf
	v_add_u32_e32 v87, -16, v197
	v_cmp_lt_i32_e32 vcc, v87, v198
	s_nop 1
	v_cndmask_b32_e32 v87, v87, v197, vcc
	v_lshlrev_b32_e32 v87, 2, v87
	v_mov_b32_e32 v90, v88
	s_waitcnt lgkmcnt(0)
	s_nop 1
	v_add_u32_dpp v90, v90, v90 row_bcast:15 row_mask:0xa bank_mask:0xf
	v_subrev_u32_e32 v88, 32, v197
	v_cmp_lt_i32_e32 vcc, v88, v198
	s_nop 1
	v_cndmask_b32_e32 v88, v88, v197, vcc
	v_lshlrev_b32_e32 v88, 2, v88
	s_nop 0
	s_waitcnt lgkmcnt(0)
	s_nop 1
	v_add_u32_dpp v90, v90, v90 row_bcast:31 row_mask:0xc bank_mask:0xf
	v_sub_u32_e32 v89, v90, v89
	v_cmp_gt_u32_e32 vcc, s79, v89
	v_cmp_lt_u32_e64 s[0:1], s0, v90
	s_and_b64 s[0:1], s[0:1], vcc
	s_nop 0
	v_cndmask_b32_e64 v90, 0, 1, s[0:1]
	v_cmp_ne_u32_e32 vcc, 0, v90
	s_ff1_i32_b64 s0, vcc
	s_cmp_lg_u64 vcc, 0
	s_cselect_b32 s0, s0, 63
	v_or_b32_e32 v90, s0, v198
	v_lshlrev_b32_e32 v90, 2, v90
	ds_bpermute_b32 v89, v90, v89
	s_lshl_b32 s0, s0, 5
	s_xor_b32 s15, s0, 0x7ff
	s_and_saveexec_b64 s[0:1], s[46:47]
	s_cbranch_execz .LBB0_461
	v_sub_u32_e32 v82, s15, v180
	v_lshlrev_b32_e32 v90, 1, v82
	v_and_b32_e32 v90, -4, v90
	v_add_u32_e32 v90, s13, v90
	ds_read_b32 v90, v90
	v_and_b32_e32 v82, 1, v82
	v_cmp_eq_u32_e32 vcc, 0, v82
	s_waitcnt lgkmcnt(0)
	s_nop 0
	v_cndmask_b32_sdwa v82, v90, v90, vcc dst_sel:DWORD dst_unused:UNUSED_PAD src0_sel:WORD_1 src1_sel:WORD_0
.LBB0_461:
	s_or_b64 exec, exec, s[0:1]
	v_mov_b32_e32 v83, v82
	s_waitcnt lgkmcnt(0)
	s_nop 1
	v_add_u32_dpp v83, v83, v83 row_shr:1 row_mask:0xf bank_mask:0xf
	s_nop 0
	s_waitcnt lgkmcnt(0)
	s_nop 1
	v_add_u32_dpp v83, v83, v83 row_shr:2 row_mask:0xf bank_mask:0xf
	s_nop 0
	s_waitcnt lgkmcnt(0)
	s_nop 1
	v_add_u32_dpp v83, v83, v83 row_shr:4 row_mask:0xf bank_mask:0xf
	s_nop 0
	s_waitcnt lgkmcnt(0)
	s_nop 1
	v_add_u32_dpp v83, v83, v83 row_shr:8 row_mask:0xf bank_mask:0xf
	v_mov_b32_e32 v84, v83
	s_waitcnt lgkmcnt(0)
	s_nop 1
	v_add_u32_dpp v84, v84, v84 row_bcast:15 row_mask:0xa bank_mask:0xf
	s_nop 0
	v_sub_u32_e32 v83, 0x100, v89
	s_waitcnt lgkmcnt(0)
	s_nop 1
	v_add_u32_dpp v84, v84, v84 row_bcast:31 row_mask:0xc bank_mask:0xf
	v_sub_u32_e32 v82, v84, v82
	v_cmp_le_u32_e32 vcc, v83, v84
	v_cmp_lt_u32_e64 s[0:1], v82, v83
	s_and_b64 s[0:1], vcc, s[0:1]
	s_nop 0
	v_cndmask_b32_e64 v84, 0, 1, s[0:1]
	v_cmp_ne_u32_e32 vcc, 0, v84
	s_ff1_i32_b64 s0, vcc
	s_cmp_lg_u64 vcc, 0
	s_cselect_b32 s13, s0, 63
	v_or_b32_e32 v84, s13, v198
	v_lshlrev_b32_e32 v84, 2, v84
	ds_bpermute_b32 v82, v84, v82
	s_and_saveexec_b64 s[0:1], s[36:37]
	s_cbranch_execz .LBB0_463
	s_sub_i32 s13, s15, s13
	s_lshl_b32 s15, s14, 2
	s_add_i32 s15, s15, 0
	s_add_i32 s19, s15, 0x20180
	s_waitcnt lgkmcnt(0)
	v_sub_u32_e32 v82, v83, v82
	s_add_i32 s15, s15, 0x20200
	v_mov_b32_e32 v83, s19
	v_mov_b32_e32 v84, s13
	ds_write_b32 v83, v84
	v_mov_b32_e32 v83, s15
	ds_write_b32 v83, v82

; #define LAS __attribute__((address_space(3)))
; __device__ __forceinline__ void wave_find(unsigned c, unsigned need, int lane, int& sl, unsigned& excl_at) {
;     unsigned incl = c;
; #pragma unroll
;     for (int o = 1; o < 64; o <<= 1) { const unsigned t = __shfl_up(incl, o); if (lane >= o) incl += t; }
;     const unsigned excl = incl - c;
;     const unsigned long long b = __builtin_amdgcn_ballot_w64(excl < need && need <= incl);
;     sl = b ? (int)__builtin_ctzll(b) : 63;
;     excl_at = __shfl(excl, sl);
; }
; __device__ __forceinline__ bool indexer_fast(LAS unsigned char* lds, const bf16_t* H, unsigned char* MASKB, int bl, int qb) {
;     ...
;     for (int r = 0; r < 4; ++r) {
;         const int row = wid * 4 + r;
;         if (q0 + row < 256) { if (lane == 0) { tbin[row] = -1; need1[row] = 0u; } continue; }
;         const LAS unsigned* hp = H11 + row * 1025 + 1008 - 16 * lane;
;         unsigned c = 0u;
; #pragma unroll
;         for (int i = 0; i < 16; ++i) { const unsigned w = hp[i]; c += (w & 0xffffu) + (w >> 16); }
;         int L1; unsigned ex1; wave_find(c, 256u, lane, L1, ex1);
;         const int top = 2047 - 32 * L1; const unsigned need2 = 256u - ex1;
;         unsigned c2 = 0u;
;         if (lane < 32) { const int bin = top - lane; const unsigned w = H11[row * 1025 + (bin >> 1)]; c2 = (bin & 1) ? (w >> 16) : (w & 0xffffu); }
;         int L2; unsigned ex2; wave_find(c2, need2, lane, L2, ex2);
;         if (lane == 0) { tbin[row] = top - L2; need1[row] = need2 - ex2; }
;     }
.LBB0_468:
	s_or_b32 s15, s16, 2
	s_add_i32 s0, s15, s17
	s_cmpk_lt_i32 s0, 0x100
	s_mov_b64 s[0:1], -1
	s_cbranch_scc1 .LBB0_474
	s_mul_i32 s0, s15, 0x1004
	s_add_i32 s13, s0, 0
	v_add_u32_e32 v86, s13, v0
	s_waitcnt lgkmcnt(0)
	v_add_u32_e32 v82, 0xfc0, v86
	ds_read2_b64 v[82:85], v82 offset1:1
	s_movk_i32 s0, 0xff
	s_waitcnt lgkmcnt(0)
	v_add_u32_sdwa v82, v82, v82 dst_sel:DWORD dst_unused:UNUSED_PAD src0_sel:WORD_1 src1_sel:WORD_0
	v_and_b32_e32 v87, 0xffff, v83
	v_lshrrev_b32_e32 v83, 16, v83
	v_add3_u32 v82, v82, v83, v87
	v_and_b32_e32 v83, 0xffff, v84
	v_lshrrev_b32_e32 v84, 16, v84
	v_add3_u32 v82, v82, v84, v83
	v_and_b32_e32 v83, 0xffff, v85
	v_lshrrev_b32_e32 v84, 16, v85
	v_add3_u32 v87, v82, v84, v83
	v_add_u32_e32 v82, 0xfd0, v86
	ds_read2_b64 v[82:85], v82 offset1:1
	s_waitcnt lgkmcnt(0)
	v_and_b32_e32 v88, 0xffff, v82
	v_lshrrev_b32_e32 v82, 16, v82
	v_add3_u32 v82, v87, v82, v88
	v_and_b32_e32 v87, 0xffff, v83
	v_lshrrev_b32_e32 v83, 16, v83
	v_add3_u32 v82, v82, v83, v87
	v_and_b32_e32 v83, 0xffff, v84
	v_lshrrev_b32_e32 v84, 16, v84
	v_add3_u32 v82, v82, v84, v83
	v_and_b32_e32 v83, 0xffff, v85
	v_lshrrev_b32_e32 v84, 16, v85
	v_add3_u32 v87, v82, v84, v83
	v_add_u32_e32 v82, 0xfe0, v86
	ds_read2_b64 v[82:85], v82 offset1:1
	s_waitcnt lgkmcnt(0)
	v_and_b32_e32 v88, 0xffff, v82
	v_lshrrev_b32_e32 v82, 16, v82
	v_add3_u32 v82, v87, v82, v88
	v_and_b32_e32 v87, 0xffff, v83
	v_lshrrev_b32_e32 v83, 16, v83
	v_add3_u32 v82, v82, v83, v87
	v_and_b32_e32 v83, 0xffff, v84
	v_lshrrev_b32_e32 v84, 16, v84
	v_add3_u32 v82, v82, v84, v83
	v_and_b32_e32 v83, 0xffff, v85
	v_lshrrev_b32_e32 v84, 16, v85
	v_add3_u32 v87, v82, v84, v83
	v_add_u32_e32 v82, 0xff0, v86
	ds_read2_b64 v[82:85], v82 offset1:1
	s_waitcnt lgkmcnt(0)
	v_and_b32_e32 v86, 0xffff, v82
	v_lshrrev_b32_e32 v82, 16, v82
	v_add3_u32 v82, v87, v82, v86
	v_and_b32_e32 v86, 0xffff, v83
	v_lshrrev_b32_e32 v83, 16, v83
	v_add3_u32 v82, v82, v83, v86
	v_and_b32_e32 v83, 0xffff, v84
	v_lshrrev_b32_e32 v84, 16, v84
	v_add3_u32 v82, v82, v84, v83
	v_and_b32_e32 v83, 0xffff, v85
	v_lshrrev_b32_e32 v84, 16, v85
	v_add3_u32 v89, v82, v84, v83
	v_add_u32_e32 v83, -1, v197
	v_cmp_lt_i32_e32 vcc, v83, v198
	v_mov_b32_e32 v82, 0
	s_nop 0
	v_cndmask_b32_e32 v83, v83, v197, vcc
	v_lshlrev_b32_e32 v83, 2, v83
	v_mov_b32_e32 v85, v89
	s_waitcnt lgkmcnt(0)
	s_nop 1
	v_add_u32_dpp v85, v85, v85 row_shr:1 row_mask:0xf bank_mask:0xf
	v_add_u32_e32 v84, -2, v197
	v_cmp_lt_i32_e32 vcc, v84, v198
	s_nop 1
	v_cndmask_b32_e32 v84, v84, v197, vcc
	v_lshlrev_b32_e32 v84, 2, v84
	v_mov_b32_e32 v86, v85
	s_waitcnt lgkmcnt(0)
	s_nop 1
	v_add_u32_dpp v86, v86, v86 row_shr:2 row_mask:0xf bank_mask:0xf
	v_add_u32_e32 v85, -4, v197
	v_cmp_lt_i32_e32 vcc, v85, v198
	s_nop 1
	v_cndmask_b32_e32 v85, v85, v197, vcc
	v_lshlrev_b32_e32 v85, 2, v85
	v_mov_b32_e32 v87, v86
	s_waitcnt lgkmcnt(0)
	s_nop 1
	v_add_u32_dpp v87, v87, v87 row_shr:4 row_mask:0xf bank_mask:0xf
	v_add_u32_e32 v86, -8, v197
	v_cmp_lt_i32_e32 vcc, v86, v198
	s_nop 1
	v_cndmask_b32_e32 v86, v86, v197, vcc
	v_lshlrev_b32_e32 v86, 2, v86
	v_mov_b32_e32 v88, v87
	s_waitcnt lgkmcnt(0)
	s_nop 1
	v_add_u32_dpp v88, v88, v88 row_shr:8 row_mask:0xf bank_mask:0xf
	v_add_u32_e32 v87, -16, v197
	v_cmp_lt_i32_e32 vcc, v87, v198
	s_nop 1
	v_cndmask_b32_e32 v87, v87, v197, vcc
	v_lshlrev_b32_e32 v87, 2, v87
	v_mov_b32_e32 v90, v88
	s_waitcnt lgkmcnt(0)
	s_nop 1
	v_add_u32_dpp v90, v90, v90 row_bcast:15 row_mask:0xa bank_mask:0xf
	v_subrev_u32_e32 v88, 32, v197
	v_cmp_lt_i32_e32 vcc, v88, v198
	s_nop 1
	v_cndmask_b32_e32 v88, v88, v197, vcc
	v_lshlrev_b32_e32 v88, 2, v88
	s_nop 0
	s_waitcnt lgkmcnt(0)
	s_nop 1
	v_add_u32_dpp v90, v90, v90 row_bcast:31 row_mask:0xc bank_mask:0xf
	v_sub_u32_e32 v89, v90, v89
	v_cmp_gt_u32_e32 vcc, s79, v89
	v_cmp_lt_u32_e64 s[0:1], s0, v90
	s_and_b64 s[0:1], s[0:1], vcc
	s_nop 0
	v_cndmask_b32_e64 v90, 0, 1, s[0:1]
	v_cmp_ne_u32_e32 vcc, 0, v90
	s_ff1_i32_b64 s0, vcc
	s_cmp_lg_u64 vcc, 0
	s_cselect_b32 s0, s0, 63
	v_or_b32_e32 v90, s0, v198
	v_lshlrev_b32_e32 v90, 2, v90
	ds_bpermute_b32 v89, v90, v89
	s_lshl_b32 s0, s0, 5
	s_xor_b32 s19, s0, 0x7ff
	s_and_saveexec_b64 s[0:1], s[46:47]
	s_cbranch_execz .LBB0_471
	v_sub_u32_e32 v82, s19, v180
	v_lshlrev_b32_e32 v90, 1, v82
	v_and_b32_e32 v90, -4, v90
	v_add_u32_e32 v90, s13, v90
	ds_read_b32 v90, v90
	v_and_b32_e32 v82, 1, v82
	v_cmp_eq_u32_e32 vcc, 0, v82
	s_waitcnt lgkmcnt(0)
	s_nop 0
	v_cndmask_b32_sdwa v82, v90, v90, vcc dst_sel:DWORD dst_unused:UNUSED_PAD src0_sel:WORD_1 src1_sel:WORD_0
.LBB0_471:
	s_or_b64 exec, exec, s[0:1]
	v_mov_b32_e32 v83, v82
	s_waitcnt lgkmcnt(0)
	s_nop 1
	v_add_u32_dpp v83, v83, v83 row_shr:1 row_mask:0xf bank_mask:0xf
	s_nop 0
	s_waitcnt lgkmcnt(0)
	s_nop 1
	v_add_u32_dpp v83, v83, v83 row_shr:2 row_mask:0xf bank_mask:0xf
	s_nop 0
	s_waitcnt lgkmcnt(0)
	s_nop 1
	v_add_u32_dpp v83, v83, v83 row_shr:4 row_mask:0xf bank_mask:0xf
	s_nop 0
	s_waitcnt lgkmcnt(0)
	s_nop 1
	v_add_u32_dpp v83, v83, v83 row_shr:8 row_mask:0xf bank_mask:0xf
	v_mov_b32_e32 v84, v83
	s_waitcnt lgkmcnt(0)
	s_nop 1
	v_add_u32_dpp v84, v84, v84 row_bcast:15 row_mask:0xa bank_mask:0xf
	s_nop 0
	v_sub_u32_e32 v83, 0x100, v89
	s_waitcnt lgkmcnt(0)
	s_nop 1
	v_add_u32_dpp v84, v84, v84 row_bcast:31 row_mask:0xc bank_mask:0xf
	v_sub_u32_e32 v82, v84, v82
	v_cmp_le_u32_e32 vcc, v83, v84
	v_cmp_lt_u32_e64 s[0:1], v82, v83
	s_and_b64 s[0:1], vcc, s[0:1]
	s_nop 0
	v_cndmask_b32_e64 v84, 0, 1, s[0:1]
	v_cmp_ne_u32_e32 vcc, 0, v84
	s_ff1_i32_b64 s0, vcc
	s_cmp_lg_u64 vcc, 0
	s_cselect_b32 s13, s0, 63
	v_or_b32_e32 v84, s13, v198
	v_lshlrev_b32_e32 v84, 2, v84
	ds_bpermute_b32 v82, v84, v82
	s_and_saveexec_b64 s[0:1], s[36:37]
	s_cbranch_execz .LBB0_473
	s_sub_i32 s13, s19, s13
	s_lshl_b32 s19, s15, 2
	s_add_i32 s19, s19, 0
	s_add_i32 s20, s19, 0x20180
	s_waitcnt lgkmcnt(0)
	v_sub_u32_e32 v82, v83, v82
	s_add_i32 s19, s19, 0x20200
	v_mov_b32_e32 v83, s20
	v_mov_b32_e32 v84, s13
	ds_write_b32 v83, v84
	v_mov_b32_e32 v83, s19
	ds_write_b32 v83, v82

; #define LAS __attribute__((address_space(3)))
; __device__ __forceinline__ void wave_find(unsigned c, unsigned need, int lane, int& sl, unsigned& excl_at) {
;     unsigned incl = c;
; #pragma unroll
;     for (int o = 1; o < 64; o <<= 1) { const unsigned t = __shfl_up(incl, o); if (lane >= o) incl += t; }
;     const unsigned excl = incl - c;
;     const unsigned long long b = __builtin_amdgcn_ballot_w64(excl < need && need <= incl);
;     sl = b ? (int)__builtin_ctzll(b) : 63;
;     excl_at = __shfl(excl, sl);
; }
; __device__ __forceinline__ bool indexer_fast(LAS unsigned char* lds, const bf16_t* H, unsigned char* MASKB, int bl, int qb) {
;     ...
;     for (int r = 0; r < 4; ++r) {
;         const int row = wid * 4 + r;
;         if (q0 + row < 256) { if (lane == 0) { tbin[row] = -1; need1[row] = 0u; } continue; }
;         const LAS unsigned* hp = H11 + row * 1025 + 1008 - 16 * lane;
;         unsigned c = 0u;
; #pragma unroll
;         for (int i = 0; i < 16; ++i) { const unsigned w = hp[i]; c += (w & 0xffffu) + (w >> 16); }
;         int L1; unsigned ex1; wave_find(c, 256u, lane, L1, ex1);
;         const int top = 2047 - 32 * L1; const unsigned need2 = 256u - ex1;
;         unsigned c2 = 0u;
;         if (lane < 32) { const int bin = top - lane; const unsigned w = H11[row * 1025 + (bin >> 1)]; c2 = (bin & 1) ? (w >> 16) : (w & 0xffffu); }
;         int L2; unsigned ex2; wave_find(c2, need2, lane, L2, ex2);
;         if (lane == 0) { tbin[row] = top - L2; need1[row] = need2 - ex2; }
;     }
.LBB0_478:
	s_or_b32 s13, s16, 3
	s_add_i32 s0, s13, s17
	s_cmpk_lt_i32 s0, 0x100
	s_mov_b64 s[0:1], -1
	s_cbranch_scc1 .LBB0_484
	s_mul_i32 s0, s13, 0x1004
	s_add_i32 s19, s0, 0
	v_add_u32_e32 v0, s19, v0
	s_waitcnt lgkmcnt(0)
	v_add_u32_e32 v82, 0xfc0, v0
	ds_read2_b32 v[82:83], v82 offset1:1
	s_movk_i32 s0, 0xff
	s_waitcnt lgkmcnt(0)
	v_add_u32_sdwa v82, v82, v82 dst_sel:DWORD dst_unused:UNUSED_PAD src0_sel:WORD_1 src1_sel:WORD_0
	v_and_b32_e32 v84, 0xffff, v83
	v_lshrrev_b32_e32 v83, 16, v83
	v_add3_u32 v84, v82, v83, v84
	v_add_u32_e32 v82, 0xfc8, v0
	ds_read2_b32 v[82:83], v82 offset1:1
	s_waitcnt lgkmcnt(0)
	v_and_b32_e32 v85, 0xffff, v82
	v_lshrrev_b32_e32 v82, 16, v82
	v_add3_u32 v82, v84, v82, v85
	v_and_b32_e32 v84, 0xffff, v83
	v_lshrrev_b32_e32 v83, 16, v83
	v_add3_u32 v84, v82, v83, v84
	v_add_u32_e32 v82, 0xfd0, v0
	ds_read2_b32 v[82:83], v82 offset1:1
	s_waitcnt lgkmcnt(0)
	v_and_b32_e32 v85, 0xffff, v82
	v_lshrrev_b32_e32 v82, 16, v82
	v_add3_u32 v82, v84, v82, v85
	v_and_b32_e32 v84, 0xffff, v83
	v_lshrrev_b32_e32 v83, 16, v83
	v_add3_u32 v84, v82, v83, v84
	v_add_u32_e32 v82, 0xfd8, v0
	ds_read2_b32 v[82:83], v82 offset1:1
	s_waitcnt lgkmcnt(0)
	v_and_b32_e32 v85, 0xffff, v82
	v_lshrrev_b32_e32 v82, 16, v82
	v_add3_u32 v82, v84, v82, v85
	v_and_b32_e32 v84, 0xffff, v83
	v_lshrrev_b32_e32 v83, 16, v83
	v_add3_u32 v84, v82, v83, v84
	v_add_u32_e32 v82, 0xfe0, v0
	ds_read2_b32 v[82:83], v82 offset1:1
	s_waitcnt lgkmcnt(0)
	v_and_b32_e32 v85, 0xffff, v82
	v_lshrrev_b32_e32 v82, 16, v82
	v_add3_u32 v82, v84, v82, v85
	v_and_b32_e32 v84, 0xffff, v83
	v_lshrrev_b32_e32 v83, 16, v83
	v_add3_u32 v84, v82, v83, v84
	v_add_u32_e32 v82, 0xfe8, v0
	ds_read2_b32 v[82:83], v82 offset1:1
	s_waitcnt lgkmcnt(0)
	v_and_b32_e32 v85, 0xffff, v82
	v_lshrrev_b32_e32 v82, 16, v82
	v_add3_u32 v82, v84, v82, v85
	v_and_b32_e32 v84, 0xffff, v83
	v_lshrrev_b32_e32 v83, 16, v83
	v_add3_u32 v84, v82, v83, v84
	v_add_u32_e32 v82, 0xff0, v0
	ds_read2_b32 v[82:83], v82 offset1:1
	v_add_u32_e32 v0, 0xff8, v0
	s_waitcnt lgkmcnt(0)
	v_and_b32_e32 v85, 0xffff, v82
	v_lshrrev_b32_e32 v82, 16, v82
	v_add3_u32 v82, v84, v82, v85
	v_and_b32_e32 v84, 0xffff, v83
	v_lshrrev_b32_e32 v83, 16, v83
	v_add3_u32 v84, v82, v83, v84
	ds_read2_b32 v[82:83], v0 offset1:1
	s_waitcnt lgkmcnt(0)
	v_and_b32_e32 v0, 0xffff, v82
	v_lshrrev_b32_e32 v82, 16, v82
	v_add3_u32 v0, v84, v82, v0
	v_and_b32_e32 v82, 0xffff, v83
	v_lshrrev_b32_e32 v83, 16, v83
	v_add3_u32 v88, v0, v83, v82
	v_add_u32_e32 v82, -1, v197
	v_cmp_lt_i32_e32 vcc, v82, v198
	v_mov_b32_e32 v0, 0
	s_nop 0
	v_cndmask_b32_e32 v82, v82, v197, vcc
	v_lshlrev_b32_e32 v82, 2, v82
	v_mov_b32_e32 v84, v88
	s_waitcnt lgkmcnt(0)
	s_nop 1
	v_add_u32_dpp v84, v84, v84 row_shr:1 row_mask:0xf bank_mask:0xf
	v_add_u32_e32 v83, -2, v197
	v_cmp_lt_i32_e32 vcc, v83, v198
	s_nop 1
	v_cndmask_b32_e32 v83, v83, v197, vcc
	v_lshlrev_b32_e32 v83, 2, v83
	v_mov_b32_e32 v85, v84
	s_waitcnt lgkmcnt(0)
	s_nop 1
	v_add_u32_dpp v85, v85, v85 row_shr:2 row_mask:0xf bank_mask:0xf
	v_add_u32_e32 v84, -4, v197
	v_cmp_lt_i32_e32 vcc, v84, v198
	s_nop 1
	v_cndmask_b32_e32 v84, v84, v197, vcc
	v_lshlrev_b32_e32 v84, 2, v84
	v_mov_b32_e32 v86, v85
	s_waitcnt lgkmcnt(0)
	s_nop 1
	v_add_u32_dpp v86, v86, v86 row_shr:4 row_mask:0xf bank_mask:0xf
	v_add_u32_e32 v85, -8, v197
	v_cmp_lt_i32_e32 vcc, v85, v198
	s_nop 1
	v_cndmask_b32_e32 v85, v85, v197, vcc
	v_lshlrev_b32_e32 v85, 2, v85
	v_mov_b32_e32 v87, v86
	s_waitcnt lgkmcnt(0)
	s_nop 1
	v_add_u32_dpp v87, v87, v87 row_shr:8 row_mask:0xf bank_mask:0xf
	v_add_u32_e32 v86, -16, v197
	v_cmp_lt_i32_e32 vcc, v86, v198
	s_nop 1
	v_cndmask_b32_e32 v86, v86, v197, vcc
	v_lshlrev_b32_e32 v86, 2, v86
	v_mov_b32_e32 v89, v87
	s_waitcnt lgkmcnt(0)
	s_nop 1
	v_add_u32_dpp v89, v89, v89 row_bcast:15 row_mask:0xa bank_mask:0xf
	v_subrev_u32_e32 v87, 32, v197
	v_cmp_lt_i32_e32 vcc, v87, v198
	s_nop 1
	v_cndmask_b32_e32 v87, v87, v197, vcc
	v_lshlrev_b32_e32 v87, 2, v87
	s_nop 0
	s_waitcnt lgkmcnt(0)
	s_nop 1
	v_add_u32_dpp v89, v89, v89 row_bcast:31 row_mask:0xc bank_mask:0xf
	v_sub_u32_e32 v88, v89, v88
	v_cmp_gt_u32_e32 vcc, s79, v88
	v_cmp_lt_u32_e64 s[0:1], s0, v89
	s_and_b64 s[0:1], s[0:1], vcc
	s_nop 0
	v_cndmask_b32_e64 v89, 0, 1, s[0:1]
	v_cmp_ne_u32_e32 vcc, 0, v89
	s_ff1_i32_b64 s0, vcc
	s_cmp_lg_u64 vcc, 0
	s_cselect_b32 s0, s0, 63
	v_or_b32_e32 v89, s0, v198
	v_lshlrev_b32_e32 v89, 2, v89
	ds_bpermute_b32 v88, v89, v88
	s_lshl_b32 s0, s0, 5
	s_xor_b32 s20, s0, 0x7ff
	s_and_saveexec_b64 s[0:1], s[46:47]
	s_cbranch_execz .LBB0_481
	v_sub_u32_e32 v0, s20, v180
	v_lshlrev_b32_e32 v89, 1, v0
	v_and_b32_e32 v89, -4, v89
	v_add_u32_e32 v89, s19, v89
	ds_read_b32 v89, v89
	v_and_b32_e32 v0, 1, v0
	v_cmp_eq_u32_e32 vcc, 0, v0
	s_waitcnt lgkmcnt(0)
	s_nop 0
	v_cndmask_b32_sdwa v0, v89, v89, vcc dst_sel:DWORD dst_unused:UNUSED_PAD src0_sel:WORD_1 src1_sel:WORD_0
.LBB0_481:
	s_or_b64 exec, exec, s[0:1]
	v_mov_b32_e32 v82, v0
	s_waitcnt lgkmcnt(0)
	s_nop 1
	v_add_u32_dpp v82, v82, v82 row_shr:1 row_mask:0xf bank_mask:0xf
	s_nop 0
	s_waitcnt lgkmcnt(0)
	s_nop 1
	v_add_u32_dpp v82, v82, v82 row_shr:2 row_mask:0xf bank_mask:0xf
	s_nop 0
	s_waitcnt lgkmcnt(0)
	s_nop 1
	v_add_u32_dpp v82, v82, v82 row_shr:4 row_mask:0xf bank_mask:0xf
	s_nop 0
	s_waitcnt lgkmcnt(0)
	s_nop 1
	v_add_u32_dpp v82, v82, v82 row_shr:8 row_mask:0xf bank_mask:0xf
	v_mov_b32_e32 v83, v82
	s_waitcnt lgkmcnt(0)
	s_nop 1
	v_add_u32_dpp v83, v83, v83 row_bcast:15 row_mask:0xa bank_mask:0xf
	s_nop 0
	v_sub_u32_e32 v82, 0x100, v88
	s_waitcnt lgkmcnt(0)
	s_nop 1
	v_add_u32_dpp v83, v83, v83 row_bcast:31 row_mask:0xc bank_mask:0xf
	v_sub_u32_e32 v0, v83, v0
	v_cmp_le_u32_e32 vcc, v82, v83
	v_cmp_lt_u32_e64 s[0:1], v0, v82
	s_and_b64 s[0:1], vcc, s[0:1]
	s_nop 0
	v_cndmask_b32_e64 v83, 0, 1, s[0:1]
	v_cmp_ne_u32_e32 vcc, 0, v83
	s_ff1_i32_b64 s0, vcc
	s_cmp_lg_u64 vcc, 0
	s_cselect_b32 s19, s0, 63
	v_or_b32_e32 v83, s19, v198
	v_lshlrev_b32_e32 v83, 2, v83
	ds_bpermute_b32 v0, v83, v0
	s_and_saveexec_b64 s[0:1], s[36:37]
	s_cbranch_execz .LBB0_483
	s_sub_i32 s19, s20, s19
	s_lshl_b32 s20, s13, 2
	s_add_i32 s20, s20, 0
	s_add_i32 s21, s20, 0x20180
	s_waitcnt lgkmcnt(0)
	v_sub_u32_e32 v0, v82, v0
	s_add_i32 s20, s20, 0x20200
	v_mov_b32_e32 v82, s21
	v_mov_b32_e32 v83, s19
	ds_write_b32 v82, v83
	v_mov_b32_e32 v82, s20
	ds_write_b32 v82, v0

; __device__ __forceinline__ u32x4 pack8(const float (&f)[8]) { u32x4 w; w.x = pk2(f[0], f[1]); w.y = pk2(f[2], f[3]); w.z = pk2(f[4], f[5]); w.w = pk2(f[6], f[7]); return w; }
; __device__ __forceinline__ void norm_phase(const Params& p, bf16_t* H, int Tc, int l) {
;     ...
;     for (int row = gw; row < Tc; row += nw) {
;         bf16_t* ptr = H + (size_t)row * NP1 + (isq ? CQ + lane * 8 : CKV + (lane - 32) * 8);
;         u32x4 w = act ? *(const u32x4*)ptr : (u32x4){0u, 0u, 0u, 0u};
;         float f[8]; unpack8(w, f); float ss = 0.f;
; #pragma unroll
;         for (int i = 0; i < 8; ++i) ss += f[i] * f[i];
;         ss += __shfl_xor(ss, 1); ss += __shfl_xor(ss, 2); ss += __shfl_xor(ss, 4); ss += __shfl_xor(ss, 8);
;         const float s16 = __shfl_xor(ss, 16);
;         if (isq) ss += s16;
;         const float rs = rsqrtf(ss * (isq ? (1.0f / 256.0f) : (1.0f / 128.0f)) + 1e-6f);
; #pragma unroll
;         for (int i = 0; i < 8; ++i) f[i] = f[i] * rs * (isq ? gCq[i] : gCkv[i]);
;         if (act) *(u32x4*)ptr = pack8(f);
.LBB0_747:
	s_or_b64 exec, exec, s[0:1]
	s_waitcnt vmcnt(0)
	v_and_b32_e32 v25, 0xffff0000, v2
	v_lshlrev_b32_e32 v26, 16, v2
	v_lshlrev_b32_e32 v24, 16, v3
	v_and_b32_e32 v23, 0xffff0000, v3
	v_lshlrev_b32_e32 v3, 16, v4
	v_and_b32_e32 v2, 0xffff0000, v4
	v_lshlrev_b32_e32 v0, 16, v5
	v_and_b32_e32 v4, 0xffff0000, v5
	v_mul_f32_e32 v5, v25, v25
	v_fmac_f32_e32 v5, v26, v26
	v_fmac_f32_e32 v5, v24, v24
	v_fmac_f32_e32 v5, v23, v23
	v_fmac_f32_e32 v5, v3, v3
	v_fmac_f32_e32 v5, v2, v2
	v_fmac_f32_e32 v5, v0, v0
	v_fmac_f32_e32 v5, v4, v4
	s_waitcnt lgkmcnt(0)
	s_nop 1
	v_add_f32_dpp v5, v5, v5 quad_perm:[1,0,3,2] row_mask:0xf bank_mask:0xf
	s_nop 1
	v_add_f32_dpp v5, v5, v5 quad_perm:[2,3,0,1] row_mask:0xf bank_mask:0xf
	s_nop 1
	v_add_f32_dpp v5, v5, v5 row_half_mirror row_mask:0xf bank_mask:0xf
	s_nop 1
	v_add_f32_dpp v5, v5, v5 row_mirror row_mask:0xf bank_mask:0xf
	s_nop 0
	ds_bpermute_b32 v27, v13, v5
	s_and_saveexec_b64 s[40:41], s[36:37]
	s_cbranch_execz .LBB0_744
	s_waitcnt lgkmcnt(0)
	v_add_f32_e32 v27, v5, v27
	v_cndmask_b32_e32 v5, v5, v27, vcc
	v_fmaak_f32 v5, v14, v5, 0x358637bd
	v_mul_f32_e32 v27, 0x4b800000, v5
	v_cmp_gt_f32_e64 s[0:1], s68, v5
	s_nop 1
	v_cndmask_b32_e64 v5, v5, v27, s[0:1]
	v_rsq_f32_e32 v5, v5
	s_nop 0
	v_mul_f32_e32 v27, 0x45800000, v5
	v_cndmask_b32_e64 v5, v5, v27, s[0:1]
	v_mul_f32_e32 v4, v5, v4
	v_mul_f32_e32 v26, v5, v26
	v_mul_f32_e32 v27, v15, v4
	v_mul_f32_e32 v4, v16, v26
	v_mul_f32_e32 v25, v5, v25
	v_mul_f32_e32 v24, v5, v24
	v_mul_f32_e32 v23, v5, v23
	v_mul_f32_e32 v3, v5, v3
	v_mul_f32_e32 v2, v5, v2
	v_mul_f32_e32 v0, v5, v0
	v_mul_f32_e32 v25, v17, v25
	v_mul_f32_e32 v24, v18, v24
	v_mul_f32_e32 v23, v19, v23
	v_mul_f32_e32 v26, v20, v3
	v_mul_f32_e32 v28, v21, v2
	v_mul_f32_e32 v0, v22, v0
	v_cvt_pk_bf16_f32 v2, v4, v25
	v_cvt_pk_bf16_f32 v3, v24, v23
	v_cvt_pk_bf16_f32 v4, v26, v28
	v_cvt_pk_bf16_f32 v5, v0, v27
	global_store_dwordx4 v[6:7], v[2:5], off
	s_branch .LBB0_744
